# v27
# speedup vs baseline: 1.0106x; 1.0106x over previous
; DEVI void attn_unit(const Params& p, char* lds, int au) {
;     ...
; #pragma unroll
;     for (int qb = 0; qb < 2; ++qb) {
;       u32x4 t0, t1;
; #pragma unroll
;       for (int kb = 0; kb < 4; ++kb) {
;         f32x4 e;
;         e[0] = __builtin_amdgcn_exp2f(sc[kb][qb][0]);
;         e[1] = __builtin_amdgcn_exp2f(sc[kb][qb][1]);
;         e[2] = __builtin_amdgcn_exp2f(sc[kb][qb][2]);
;         e[3] = __builtin_amdgcn_exp2f(sc[kb][qb][3]);
;         lsum[qb] += e;
;         uint32_t w0 = pk2(e[0], e[1]), w1 = pk2(e[2], e[3]);
;         if (kb == 0) { t0[0] = w0; t0[1] = w1; }
;         if (kb == 1) { t0[2] = w0; t0[3] = w1; }
;         if (kb == 2) { t1[0] = w0; t1[1] = w1; }
;         if (kb == 3) { t1[2] = w0; t1[3] = w1; }
;       }
;       pf[qb][0] = __builtin_bit_cast(bf16x8, t0);
;       pf[qb][1] = __builtin_bit_cast(bf16x8, t1);
;     }
;     if (!typeB) PVSTEP(lds + 32768 + vcur * 16384);
.LBB0_217:
	v_exp_f32_e32 v146, v90
	v_exp_f32_e32 v147, v91
	v_exp_f32_e32 v148, v92
	v_exp_f32_e32 v149, v93
	v_exp_f32_e32 v118, v118
	v_exp_f32_e32 v119, v119
	v_exp_f32_e32 v120, v120
	v_exp_f32_e32 v121, v121
	v_exp_f32_e32 v150, v98
	v_exp_f32_e32 v151, v99
	v_exp_f32_e32 v152, v100
	v_exp_f32_e32 v153, v101
	v_exp_f32_e32 v114, v114
	v_exp_f32_e32 v115, v115
	v_exp_f32_e32 v116, v116
	v_exp_f32_e32 v117, v117
	v_exp_f32_e32 v154, v110
	v_exp_f32_e32 v155, v111
	v_exp_f32_e32 v156, v112
	v_exp_f32_e32 v157, v113
	v_exp_f32_e32 v106, v106
	v_exp_f32_e32 v107, v107
	v_exp_f32_e32 v108, v108
	v_exp_f32_e32 v109, v109
	v_exp_f32_e32 v158, v102
	v_exp_f32_e32 v159, v103
	v_exp_f32_e32 v160, v104
	v_exp_f32_e32 v161, v105
	v_exp_f32_e32 v94, v94
	v_exp_f32_e32 v95, v95
	v_exp_f32_e32 v96, v96
	v_exp_f32_e32 v97, v97
	v_cvt_pk_bf16_f32 v90, v146, v147
	v_cvt_pk_bf16_f32 v91, v148, v149
	v_cvt_pk_bf16_f32 v92, v118, v119
	v_cvt_pk_bf16_f32 v93, v120, v121
	v_cvt_pk_bf16_f32 v98, v150, v151
	v_cvt_pk_bf16_f32 v99, v152, v153
	v_cvt_pk_bf16_f32 v100, v114, v115
	v_cvt_pk_bf16_f32 v101, v116, v117
	v_cvt_pk_bf16_f32 v110, v154, v155
	v_cvt_pk_bf16_f32 v111, v156, v157
	v_cvt_pk_bf16_f32 v112, v106, v107
	v_cvt_pk_bf16_f32 v113, v108, v109
	v_cvt_pk_bf16_f32 v102, v158, v159
	v_cvt_pk_bf16_f32 v103, v160, v161
	v_cvt_pk_bf16_f32 v104, v94, v95
	s_and_b64 vcc, exec, s[12:13]
	v_cvt_pk_bf16_f32 v105, v96, v97
	s_cbranch_vccnz .LBB0_219
	s_waitcnt lgkmcnt(4)
	v_mfma_f32_16x16x32_bf16 v[82:85], v[168:171], v[90:93], v[82:85]
	v_mfma_f32_16x16x32_bf16 v[78:81], v[168:171], v[110:113], v[78:81]
	v_mfma_f32_16x16x32_bf16 v[74:77], v[186:189], v[90:93], v[74:77]
	v_mfma_f32_16x16x32_bf16 v[70:73], v[186:189], v[110:113], v[70:73]
	v_mfma_f32_16x16x32_bf16 v[66:69], v[198:201], v[90:93], v[66:69]
	v_mfma_f32_16x16x32_bf16 v[58:61], v[198:201], v[110:113], v[58:61]
	v_mfma_f32_16x16x32_bf16 v[54:57], v[202:205], v[90:93], v[54:57]
	v_mfma_f32_16x16x32_bf16 v[50:53], v[202:205], v[110:113], v[50:53]
	ds_read_b128 v[168:171], v163 offset:40960
	ds_read_b128 v[186:189], v163 offset:43008
	ds_read_b128 v[198:201], v163 offset:45056
	ds_read_b128 v[202:205], v163 offset:47104
	s_waitcnt lgkmcnt(4)
	v_mfma_f32_16x16x32_bf16 v[82:85], v[190:193], v[98:101], v[82:85]
	v_mfma_f32_16x16x32_bf16 v[78:81], v[190:193], v[102:105], v[78:81]
	v_mfma_f32_16x16x32_bf16 v[74:77], v[194:197], v[98:101], v[74:77]
	v_mfma_f32_16x16x32_bf16 v[70:73], v[194:197], v[102:105], v[70:73]
	v_mfma_f32_16x16x32_bf16 v[66:69], v[206:209], v[98:101], v[66:69]
	v_mfma_f32_16x16x32_bf16 v[58:61], v[206:209], v[102:105], v[58:61]
	v_mfma_f32_16x16x32_bf16 v[54:57], v[210:213], v[98:101], v[54:57]
	v_mfma_f32_16x16x32_bf16 v[50:53], v[210:213], v[102:105], v[50:53]
	ds_read_b128 v[190:193], v162 offset:40960
	ds_read_b128 v[194:197], v162 offset:43008
	ds_read_b128 v[206:209], v162 offset:45056
	ds_read_b128 v[210:213], v162 offset:47104
	s_waitcnt lgkmcnt(4)
	v_mfma_f32_16x16x32_bf16 v[46:49], v[168:171], v[90:93], v[46:49]
	v_mfma_f32_16x16x32_bf16 v[42:45], v[168:171], v[110:113], v[42:45]
	v_mfma_f32_16x16x32_bf16 v[38:41], v[186:189], v[90:93], v[38:41]
	v_mfma_f32_16x16x32_bf16 v[34:37], v[186:189], v[110:113], v[34:37]
	v_mfma_f32_16x16x32_bf16 v[30:33], v[198:201], v[90:93], v[30:33]
	v_mfma_f32_16x16x32_bf16 v[26:29], v[198:201], v[110:113], v[26:29]
	v_mfma_f32_16x16x32_bf16 v[22:25], v[202:205], v[90:93], v[22:25]
	v_mfma_f32_16x16x32_bf16 v[2:5], v[202:205], v[110:113], v[2:5]
	s_waitcnt lgkmcnt(0)
	v_mfma_f32_16x16x32_bf16 v[46:49], v[190:193], v[98:101], v[46:49]
	v_mfma_f32_16x16x32_bf16 v[42:45], v[190:193], v[102:105], v[42:45]
	v_mfma_f32_16x16x32_bf16 v[38:41], v[194:197], v[98:101], v[38:41]
	v_mfma_f32_16x16x32_bf16 v[34:37], v[194:197], v[102:105], v[34:37]
	v_mfma_f32_16x16x32_bf16 v[30:33], v[206:209], v[98:101], v[30:33]
	v_mfma_f32_16x16x32_bf16 v[26:29], v[206:209], v[102:105], v[26:29]
	v_mfma_f32_16x16x32_bf16 v[22:25], v[210:213], v[98:101], v[22:25]
	v_mfma_f32_16x16x32_bf16 v[2:5], v[210:213], v[102:105], v[2:5]
